# lora: the 8 items past the first 1024 done one n-tile per wave by workgroups 0-31 instead of a second 16-tile round on waves 0 and 4 of workgroups 0-7
# speedup vs baseline: 1.0050x; 1.0050x over previous
; #define LAS __attribute__((address_space(3)))
; __device__ __forceinline__ unsigned pk2(float lo, float hi) { f32x2 v = {lo, hi}; bf16x2_t b = __builtin_convertvector(v, bf16x2_t); return __builtin_bit_cast(unsigned, b); }
; __device__ __forceinline__ float sigmoidf_(float x) { return frcp(1.f + fexp2(-1.4426950408889634f * x)); }
;     __device__ __forceinline__ const float* in(int i) const { return (const float*)ptr(i); }
;     __device__ __forceinline__ unsigned char* ws() const { return (unsigned char*)ptr(37); }
; #define ws (p.ws())
; __device__ __forceinline__ void phase_lora(const Ctx& p, LAS unsigned char* lds) {
;     const int tid = threadIdx.x, lane = tid & 63, wave = __builtin_amdgcn_readfirstlane(tid >> 6), q = lane & 15, g = lane >> 4;
;     const bf16_t* ZRW = (const bf16_t*)(p.ws() + WS_ZRW);
;     float* DEC = (float*)(p.ws() + WS_DEC); bf16_t* AB = (bf16_t*)(p.ws() + WS_ABUF); bf16_t* GG = (bf16_t*)(p.ws() + WS_GG);
;     const bf16_t* w2T = (const bf16_t*)(p.ws() + WS_LW); const bf16_t* a2T = w2T + 512 * 64; const bf16_t* g2T = a2T + 512 * 64;
;     LAS bf16_t* X = (LAS bf16_t*)(lds + wave * 16 * 264 * 2);
;     const float* mu = p.in(17) + 1536;
;     for (int it = blockIdx.x + gridDim.x * wave; it < MR / 16; it += gridDim.x * 8) {
;         const int r0 = it * 16;
;         {
;             const int tt = lane >> 2, cq = lane & 3, row = r0 + tt;
; #pragma unroll
;             for (int j = 0; j < 8; ++j) {
;                 const int c = cq * 64 + j * 8;
;                 float m8[8], z[8];
; #pragma unroll
;                 for (int e = 0; e < 8; ++e) m8[e] = mu[c + e];
;                 zshift8(p, ZRW, row, 1536 + c, m8, z);
; #pragma unroll
;                 for (int e = 0; e < 8; ++e) z[e] = cq == 0 ? tanhf(z[e]) : (cq == 1 ? z[e] : sigmoidf_(z[e]));
;                 u32x4 w; w.x = pk2(z[0], z[1]); w.y = pk2(z[2], z[3]); w.z = pk2(z[4], z[5]); w.w = pk2(z[6], z[7]);
;                 *(LAS u32x4*)(X + tt * 264 + c) = w;
.LBB0_870:
	s_cmp_lt_i32 s36, 6
	s_cselect_b64 s[4:5], -1, 0
	s_and_b64 s[10:11], s[4:5], s[2:3]
	s_andn2_b64 vcc, exec, s[10:11]
	s_cbranch_vccnz .LBB0_1564
	s_waitcnt vmcnt(0)
	v_mov_b32_e32 v0, 0x23528
	v_mov_b32_e32 v1, 0x23488
	v_mov_b32_e32 v2, 0x23428
	v_mov_b32_e32 v3, 0x23490
	v_mov_b32_e32 v4, 0x234a0
	ds_read_b64 v[6:7], v0
	ds_read_b64 v[8:9], v1
	ds_read_b64 v[10:11], v2
	ds_read_b64 v[12:13], v3
	ds_read_b64 v[14:15], v4
	v_readfirstlane_b32 s2, v180
	s_waitcnt lgkmcnt(0)
	v_readfirstlane_b32 s12, v6
	v_readfirstlane_b32 s13, v7
	v_readfirstlane_b32 s16, v8
	v_readfirstlane_b32 s17, v9
	v_readfirstlane_b32 s18, v10
	v_readfirstlane_b32 s19, v11
	v_readfirstlane_b32 s20, v12
	v_readfirstlane_b32 s21, v13
	v_readfirstlane_b32 s22, v14
	v_readfirstlane_b32 s23, v15
	s_nop 4
	s_lshr_b32 s27, s2, 6
	s_and_b32 s2, s27, 3
	s_lshr_b32 s56, s27, 2
	s_mul_i32 s2, s2, s38
	s_add_i32 s26, s2, s28
	s_add_u32 s14, s12, 0x8340000
	s_addc_u32 s15, s13, 0
	s_add_u32 s16, s16, 0x1800
	s_addc_u32 s17, s17, 0
	s_add_u32 s24, s12, 0x3110000
	s_addc_u32 s25, s13, 0
	s_add_u32 s40, s12, 0x3120000
	s_addc_u32 s41, s13, 0
	s_add_u32 s42, s12, 0x3130000
	s_addc_u32 s43, s13, 0
	s_add_u32 s44, s12, 0x3200000
	s_addc_u32 s45, s13, 0
	s_add_u32 s46, s12, 0x4240000
	s_addc_u32 s47, s13, 0
	s_add_u32 s54, s12, 0xfd20000
	s_addc_u32 s55, s13, 0
	v_and_b32_e32 v0, 63, v180
	v_lshrrev_b32_e32 v1, 2, v0
	v_and_b32_e32 v2, 3, v0
	v_and_b32_e32 v10, 15, v0
	v_lshrrev_b32_e32 v11, 4, v0
	v_cmp_eq_u32_e32 vcc, 0, v2
	v_mov_b32_e32 v12, 0xbfb8aa3b
	v_mov_b32_e32 v13, 0x4038aa3b
	v_cndmask_b32_e32 v7, v12, v13, vcc
	v_mov_b32_e32 v12, 1.0
	v_mov_b32_e32 v13, -2.0
	v_cndmask_b32_e32 v8, v12, v13, vcc
	v_mov_b32_e32 v12, 0
	v_mov_b32_e32 v13, 1.0
	v_cndmask_b32_e32 v9, v12, v13, vcc
	v_cmp_eq_u32_e64 s[48:49], 1, v2
	s_mul_i32 s3, s27, 0x2100
	v_mul_u32_u24_e32 v6, 0x210, v1
	v_lshl_add_u32 v6, v2, 7, v6
	v_add_u32_e32 v6, s3, v6
	v_mul_u32_u24_e32 v14, 0x210, v10
	v_lshl_add_u32 v14, v11, 4, v14
	v_add_u32_e32 v14, s3, v14
	v_lshlrev_b32_e32 v5, 8, v2
	s_lshr_b32 s2, s28, 3
	s_and_b32 s2, s2, 31
	s_lshl_b32 s2, s2, 13
	v_lshlrev_b32_e32 v12, 4, v180
	v_add_u32_e32 v12, s2, v12
	v_and_b32_e32 v13, 0x7f, v180
	v_lshlrev_b32_e32 v13, 4, v13
	global_load_dwordx4 v[164:167], v12, s[24:25]
	global_load_dwordx4 v[168:171], v13, s[20:21]
	global_load_dwordx4 v[172:175], v13, s[22:23]
	s_mov_b32 s57, 0

; __device__ __forceinline__ void phase_lora(const Ctx& p, LAS unsigned char* lds) {
;     ...
;                 float m8[8], z[8];
; #pragma unroll
;                 for (int e = 0; e < 8; ++e) m8[e] = mu[c + e];
;                 zshift8(p, ZRW, row, 1536 + c, m8, z);
; #pragma unroll
;                 for (int e = 0; e < 8; ++e) z[e] = cq == 0 ? tanhf(z[e]) : (cq == 1 ? z[e] : sigmoidf_(z[e]));
;                 u32x4 w; w.x = pk2(z[0], z[1]); w.y = pk2(z[2], z[3]); w.z = pk2(z[4], z[5]); w.w = pk2(z[6], z[7]);
;                 *(LAS u32x4*)(X + tt * 264 + c) = w;
;             }
;         }
;         asm volatile("s_waitcnt lgkmcnt(0)" ::: "memory");
;         bf16x8 bx[8];
; #pragma unroll
;         for (int ks = 0; ks < 8; ++ks) bx[ks] = *(const LAS bf16x8*)(X + q * 264 + ks * 32 + 8 * g);
;         const int row = r0 + q;
;         struct WF { bf16x8 w[2], a[2], gq[4]; f32x4 w0, a0; };
;         auto ldw = [&](WF& f, int nt) {
;             const int n = nt * 16 + q, c = nt * 16 + 4 * g;
; #pragma unroll
;             for (int ks = 0; ks < 2; ++ks) { f.w[ks] = *(const bf16x8*)(w2T + n * 64 + ks * 32 + 8 * g); f.a[ks] = *(const bf16x8*)(a2T + n * 64 + ks * 32 + 8 * g); }
; #pragma unroll
;             for (int ks = 0; ks < 4; ++ks) f.gq[ks] = *(const bf16x8*)(g2T + n * 128 + ks * 32 + 8 * g);
;             f.w0 = *(const f32x4*)(p.in(18) + c); f.a0 = *(const f32x4*)(p.in(20) + c);
;         };
;         auto tile = [&](const WF& f, int nt) {
;             f32x4 aw = (f32x4){0.f, 0.f, 0.f, 0.f}, aa = aw, ag = aw;
; #pragma unroll
;             for (int ks = 0; ks < 2; ++ks) { aw = __builtin_amdgcn_mfma_f32_16x16x32_bf16(f.w[ks], bx[ks], aw, 0, 0, 0); aa = __builtin_amdgcn_mfma_f32_16x16x32_bf16(f.a[ks], bx[2 + ks], aa, 0, 0, 0); }
; #pragma unroll
;             for (int ks = 0; ks < 4; ++ks) ag = __builtin_amdgcn_mfma_f32_16x16x32_bf16(f.gq[ks], bx[4 + ks], ag, 0, 0, 0);
;             const int c = nt * 16 + 4 * g;
;             f32x4 dec; float av[4];
; #pragma unroll
;             for (int e = 0; e < 4; ++e) {
;                 const float x = f.w0[e] + aw[e];
;                 const float sp = fmaxf(-x, 0.f) + log1pf(expf(-fabsf(x)));
;                 dec[e] = expf(-expf(-sp - 0.5f));
;                 av[e] = sigmoidf_(f.a0[e] + aa[e]);
;             }
;             *(f32x4*)(DEC + (size_t)row * 512 + c) = dec;
.Llora_nf7:
	v_sub_f32_e32 v152, v152, v144
	v_sub_f32_e32 v153, v153, v145
	v_sub_f32_e32 v154, v154, v146
	v_sub_f32_e32 v155, v155, v147
	v_sub_f32_e32 v156, v156, v148
	v_sub_f32_e32 v157, v157, v149
	v_sub_f32_e32 v158, v158, v150
	v_sub_f32_e32 v159, v159, v151
	v_fmac_f32_e32 v144, v152, v136
	v_fmac_f32_e32 v145, v153, v137
	v_fmac_f32_e32 v146, v154, v138
	v_fmac_f32_e32 v147, v155, v139
	v_fmac_f32_e32 v148, v156, v140
	v_fmac_f32_e32 v149, v157, v141
	v_fmac_f32_e32 v150, v158, v142
	v_fmac_f32_e32 v151, v159, v143
	v_mul_f32_e32 v152, v7, v144
	v_mul_f32_e32 v153, v7, v145
	v_mul_f32_e32 v154, v7, v146
	v_mul_f32_e32 v155, v7, v147
	v_mul_f32_e32 v156, v7, v148
	v_mul_f32_e32 v157, v7, v149
	v_mul_f32_e32 v158, v7, v150
	v_mul_f32_e32 v159, v7, v151
	v_exp_f32_e32 v152, v152
	v_exp_f32_e32 v153, v153
	v_exp_f32_e32 v154, v154
	v_exp_f32_e32 v155, v155
	v_exp_f32_e32 v156, v156
	v_exp_f32_e32 v157, v157
	v_exp_f32_e32 v158, v158
	v_exp_f32_e32 v159, v159
	v_add_f32_e32 v152, 1.0, v152
	v_add_f32_e32 v153, 1.0, v153
	v_add_f32_e32 v154, 1.0, v154
	v_add_f32_e32 v155, 1.0, v155
	v_add_f32_e32 v156, 1.0, v156
	v_add_f32_e32 v157, 1.0, v157
	v_add_f32_e32 v158, 1.0, v158
	v_add_f32_e32 v159, 1.0, v159
	v_rcp_f32_e32 v152, v152
	v_rcp_f32_e32 v153, v153
	v_rcp_f32_e32 v154, v154
	v_rcp_f32_e32 v155, v155
	v_rcp_f32_e32 v156, v156
	v_rcp_f32_e32 v157, v157
	v_rcp_f32_e32 v158, v158
	v_rcp_f32_e32 v159, v159
	v_fma_f32 v152, v152, v8, v9
	v_fma_f32 v153, v153, v8, v9
	v_fma_f32 v154, v154, v8, v9
	v_fma_f32 v155, v155, v8, v9
	v_fma_f32 v156, v156, v8, v9
	v_fma_f32 v157, v157, v8, v9
	v_fma_f32 v158, v158, v8, v9
	v_fma_f32 v159, v159, v8, v9
	v_cndmask_b32_e64 v152, v152, v144, s[48:49]
	v_cndmask_b32_e64 v153, v153, v145, s[48:49]
	v_cndmask_b32_e64 v154, v154, v146, s[48:49]
	v_cndmask_b32_e64 v155, v155, v147, s[48:49]
	v_cndmask_b32_e64 v156, v156, v148, s[48:49]
	v_cndmask_b32_e64 v157, v157, v149, s[48:49]
	v_cndmask_b32_e64 v158, v158, v150, s[48:49]
	v_cndmask_b32_e64 v159, v159, v151, s[48:49]
	v_cvt_pk_bf16_f32 v160, v152, v153
	v_cvt_pk_bf16_f32 v161, v154, v155
	v_cvt_pk_bf16_f32 v162, v156, v157
	v_cvt_pk_bf16_f32 v163, v158, v159
	ds_write_b128 v6, v[160:163] offset:112
	s_waitcnt lgkmcnt(0)
	ds_read_b128 v[184:187], v14 offset:0
	ds_read_b128 v[188:191], v14 offset:64
	ds_read_b128 v[192:195], v14 offset:128
	ds_read_b128 v[196:199], v14 offset:192
	ds_read_b128 v[200:203], v14 offset:256
	ds_read_b128 v[204:207], v14 offset:320
	ds_read_b128 v[208:211], v14 offset:384
	ds_read_b128 v[212:215], v14 offset:448
	s_lshl_b32 s2, s26, 4
	v_add_u32_e32 v137, s2, v10
	v_lshlrev_b32_e32 v132, 7, v10
	v_lshl_add_u32 v132, v11, 4, v132
	v_lshlrev_b32_e32 v133, 8, v10
	v_lshl_add_u32 v133, v11, 4, v133
	v_lshlrev_b32_e32 v134, 4, v11
	v_lshlrev_b32_e32 v135, 11, v137
	v_lshl_add_u32 v135, v11, 4, v135
	v_lshlrev_b32_e32 v136, 10, v137
	v_lshl_add_u32 v136, v11, 3, v136
	s_cmp_lg_u32 s57, 0
	s_cbranch_scc1 .Llora_single
	s_lshl_b32 s2, s56, 15
	v_add_u32_e32 v132, s2, v132
	s_lshl_b32 s2, s56, 16
	v_add_u32_e32 v133, s2, v133
	s_lshl_b32 s2, s56, 10
	v_add_u32_e32 v134, s2, v134
	v_add_u32_e32 v135, s2, v135
	s_lshl_b32 s2, s56, 9
	v_add_u32_e32 v136, s2, v136
	global_load_dwordx4 v[16:19], v132, s[24:25]
	global_load_dwordx4 v[20:23], v132, s[24:25] offset:64
	global_load_dwordx4 v[24:27], v132, s[40:41]
	global_load_dwordx4 v[28:31], v132, s[40:41] offset:64
	global_load_dwordx4 v[32:35], v133, s[42:43]
	global_load_dwordx4 v[36:39], v133, s[42:43] offset:64
	global_load_dwordx4 v[40:43], v133, s[42:43] offset:128
	global_load_dwordx4 v[44:47], v133, s[42:43] offset:192
	global_load_dwordx4 v[48:51], v134, s[20:21]
	global_load_dwordx4 v[52:55], v134, s[22:23]
	v_add_u32_e32 v132, 0x800, v132
	v_add_u32_e32 v133, 0x1000, v133
	v_add_u32_e32 v134, 64, v134
	s_waitcnt lgkmcnt(0)
	global_load_dwordx4 v[56:59], v132, s[24:25]
	global_load_dwordx4 v[60:63], v132, s[24:25] offset:64
	global_load_dwordx4 v[64:67], v132, s[40:41]
	global_load_dwordx4 v[68:71], v132, s[40:41] offset:64
	global_load_dwordx4 v[72:75], v133, s[42:43]
	global_load_dwordx4 v[76:79], v133, s[42:43] offset:64
	global_load_dwordx4 v[80:83], v133, s[42:43] offset:128
	global_load_dwordx4 v[84:87], v133, s[42:43] offset:192
	global_load_dwordx4 v[88:91], v134, s[20:21]
	global_load_dwordx4 v[92:95], v134, s[22:23]
	s_waitcnt vmcnt(10)
; __device__ __forceinline__ unsigned pk2(float lo, float hi) { f32x2 v = {lo, hi}; bf16x2_t b = __builtin_convertvector(v, bf16x2_t); return __builtin_bit_cast(unsigned, b); }
; __device__ __forceinline__ float sigmoidf_(float x) { return frcp(1.f + fexp2(-1.4426950408889634f * x)); }
; __device__ __forceinline__ void phase_lora(const Ctx& p, LAS unsigned char* lds) {
;     ...
;         auto tile = [&](const WF& f, int nt) {
;             f32x4 aw = (f32x4){0.f, 0.f, 0.f, 0.f}, aa = aw, ag = aw;
; #pragma unroll
;             for (int ks = 0; ks < 2; ++ks) { aw = __builtin_amdgcn_mfma_f32_16x16x32_bf16(f.w[ks], bx[ks], aw, 0, 0, 0); aa = __builtin_amdgcn_mfma_f32_16x16x32_bf16(f.a[ks], bx[2 + ks], aa, 0, 0, 0); }
; #pragma unroll
;             for (int ks = 0; ks < 4; ++ks) ag = __builtin_amdgcn_mfma_f32_16x16x32_bf16(f.gq[ks], bx[4 + ks], ag, 0, 0, 0);
;             const int c = nt * 16 + 4 * g;
;             f32x4 dec; float av[4];
; #pragma unroll
;             for (int e = 0; e < 4; ++e) {
;                 const float x = f.w0[e] + aw[e];
;                 const float sp = fmaxf(-x, 0.f) + log1pf(expf(-fabsf(x)));
;                 dec[e] = expf(-expf(-sp - 0.5f));
;                 av[e] = sigmoidf_(f.a0[e] + aa[e]);
;             }
;             *(f32x4*)(DEC + (size_t)row * 512 + c) = dec;
;             *(u32x2*)(AB + (size_t)row * 512 + c) = (u32x2){pk2(av[0], av[1]), pk2(av[2], av[3])};
;             *(u32x2*)(GG + (size_t)row * 512 + c) = (u32x2){pk2(ag[0], ag[1]), pk2(ag[2], ag[3])};
;         };
	v_mfma_f32_16x16x32_bf16 v[96:99], v[16:19], v[184:187], 0
	v_mfma_f32_16x16x32_bf16 v[100:103], v[24:27], v[192:195], 0
	v_mfma_f32_16x16x32_bf16 v[104:107], v[32:35], v[200:203], 0
	v_mfma_f32_16x16x32_bf16 v[96:99], v[20:23], v[188:191], v[96:99]
	v_mfma_f32_16x16x32_bf16 v[100:103], v[28:31], v[196:199], v[100:103]
	v_mfma_f32_16x16x32_bf16 v[104:107], v[36:39], v[204:207], v[104:107]
	v_mfma_f32_16x16x32_bf16 v[104:107], v[40:43], v[208:211], v[104:107]
	v_mfma_f32_16x16x32_bf16 v[104:107], v[44:47], v[212:215], v[104:107]
	v_add_u32_e32 v132, 0x800, v132
	v_add_u32_e32 v133, 0x1000, v133
	v_add_u32_e32 v134, 64, v134
	s_nop 4
	v_add_f32_e32 v108, v48, v96
	v_add_f32_e32 v109, v49, v97
	v_add_f32_e32 v110, v50, v98
	v_add_f32_e32 v111, v51, v99
	v_add_f32_e32 v112, v52, v100
	v_add_f32_e32 v113, v53, v101
	v_add_f32_e32 v114, v54, v102
	v_add_f32_e32 v115, v55, v103
	v_mul_f32_e32 v108, 0xbfb8aa3b, v108
	v_mul_f32_e32 v109, 0xbfb8aa3b, v109
	v_mul_f32_e32 v110, 0xbfb8aa3b, v110
	v_mul_f32_e32 v111, 0xbfb8aa3b, v111
	v_mul_f32_e32 v112, 0xbfb8aa3b, v112
	v_mul_f32_e32 v113, 0xbfb8aa3b, v113
	v_mul_f32_e32 v114, 0xbfb8aa3b, v114
	v_mul_f32_e32 v115, 0xbfb8aa3b, v115
	v_exp_f32_e32 v108, v108
	v_exp_f32_e32 v109, v109
	v_exp_f32_e32 v110, v110
	v_exp_f32_e32 v111, v111
	v_exp_f32_e32 v112, v112
	v_exp_f32_e32 v113, v113
	v_exp_f32_e32 v114, v114
	v_exp_f32_e32 v115, v115
	v_add_f32_e32 v108, 1.0, v108
	v_add_f32_e32 v109, 1.0, v109
	v_add_f32_e32 v110, 1.0, v110
	v_add_f32_e32 v111, 1.0, v111
	v_add_f32_e32 v112, 1.0, v112
	v_add_f32_e32 v113, 1.0, v113
	v_add_f32_e32 v114, 1.0, v114
	v_add_f32_e32 v115, 1.0, v115
	v_rcp_f32_e32 v108, v108
	v_rcp_f32_e32 v109, v109
	v_rcp_f32_e32 v110, v110
	v_rcp_f32_e32 v111, v111
	v_rcp_f32_e32 v112, v112
	v_rcp_f32_e32 v113, v113
	v_rcp_f32_e32 v114, v114
	v_rcp_f32_e32 v115, v115
	v_mul_f32_e32 v108, 0xbf60028b, v108
	v_mul_f32_e32 v109, 0xbf60028b, v109
	v_mul_f32_e32 v110, 0xbf60028b, v110
	v_mul_f32_e32 v111, 0xbf60028b, v111
	v_cvt_pk_bf16_f32 v116, v112, v113
	v_cvt_pk_bf16_f32 v117, v114, v115
	v_exp_f32_e32 v108, v108
	v_exp_f32_e32 v109, v109
	v_exp_f32_e32 v110, v110
	v_exp_f32_e32 v111, v111
	v_cvt_pk_bf16_f32 v118, v104, v105
	v_cvt_pk_bf16_f32 v119, v106, v107
	global_store_dwordx2 v136, v[116:117], s[44:45]
	global_store_dwordx2 v136, v[118:119], s[46:47]
	global_store_dwordx4 v135, v[108:111], s[54:55]
	v_add_u32_e32 v136, 32, v136
	v_add_u32_e32 v135, 64, v135
	global_load_dwordx4 v[16:19], v132, s[24:25]
	global_load_dwordx4 v[20:23], v132, s[24:25] offset:64
	global_load_dwordx4 v[24:27], v132, s[40:41]
	global_load_dwordx4 v[28:31], v132, s[40:41] offset:64
	global_load_dwordx4 v[32:35], v133, s[42:43]
	global_load_dwordx4 v[36:39], v133, s[42:43] offset:64
	global_load_dwordx4 v[40:43], v133, s[42:43] offset:128
	global_load_dwordx4 v[44:47], v133, s[42:43] offset:192
	global_load_dwordx4 v[48:51], v134, s[20:21]
	global_load_dwordx4 v[52:55], v134, s[22:23]
	s_waitcnt vmcnt(13)
	v_mfma_f32_16x16x32_bf16 v[96:99], v[56:59], v[184:187], 0
	v_mfma_f32_16x16x32_bf16 v[100:103], v[64:67], v[192:195], 0
	v_mfma_f32_16x16x32_bf16 v[104:107], v[72:75], v[200:203], 0
	v_mfma_f32_16x16x32_bf16 v[96:99], v[60:63], v[188:191], v[96:99]
	v_mfma_f32_16x16x32_bf16 v[100:103], v[68:71], v[196:199], v[100:103]
	v_mfma_f32_16x16x32_bf16 v[104:107], v[76:79], v[204:207], v[104:107]
	v_mfma_f32_16x16x32_bf16 v[104:107], v[80:83], v[208:211], v[104:107]
	v_mfma_f32_16x16x32_bf16 v[104:107], v[84:87], v[212:215], v[104:107]
	v_add_u32_e32 v132, 0x800, v132
	v_add_u32_e32 v133, 0x1000, v133
	v_add_u32_e32 v134, 64, v134
	s_nop 4
	v_add_f32_e32 v108, v88, v96
	v_add_f32_e32 v109, v89, v97
	v_add_f32_e32 v110, v90, v98
	v_add_f32_e32 v111, v91, v99
	v_add_f32_e32 v112, v92, v100
	v_add_f32_e32 v113, v93, v101
	v_add_f32_e32 v114, v94, v102
	v_add_f32_e32 v115, v95, v103
	v_mul_f32_e32 v108, 0xbfb8aa3b, v108
	v_mul_f32_e32 v109, 0xbfb8aa3b, v109
	v_mul_f32_e32 v110, 0xbfb8aa3b, v110
	v_mul_f32_e32 v111, 0xbfb8aa3b, v111
	v_mul_f32_e32 v112, 0xbfb8aa3b, v112
	v_mul_f32_e32 v113, 0xbfb8aa3b, v113
	v_mul_f32_e32 v114, 0xbfb8aa3b, v114
	v_mul_f32_e32 v115, 0xbfb8aa3b, v115
	v_exp_f32_e32 v108, v108
	v_exp_f32_e32 v109, v109
	v_exp_f32_e32 v110, v110
	v_exp_f32_e32 v111, v111
	v_exp_f32_e32 v112, v112
	v_exp_f32_e32 v113, v113
	v_exp_f32_e32 v114, v114
	v_exp_f32_e32 v115, v115
	v_add_f32_e32 v108, 1.0, v108
	v_add_f32_e32 v109, 1.0, v109
	v_add_f32_e32 v110, 1.0, v110
	v_add_f32_e32 v111, 1.0, v111
	v_add_f32_e32 v112, 1.0, v112
	v_add_f32_e32 v113, 1.0, v113
	v_add_f32_e32 v114, 1.0, v114
	v_add_f32_e32 v115, 1.0, v115
	v_rcp_f32_e32 v108, v108
	v_rcp_f32_e32 v109, v109
	v_rcp_f32_e32 v110, v110
	v_rcp_f32_e32 v111, v111
	v_rcp_f32_e32 v112, v112
	v_rcp_f32_e32 v113, v113
	v_rcp_f32_e32 v114, v114
	v_rcp_f32_e32 v115, v115
	v_mul_f32_e32 v108, 0xbf60028b, v108
	v_mul_f32_e32 v109, 0xbf60028b, v109
	v_mul_f32_e32 v110, 0xbf60028b, v110
	v_mul_f32_e32 v111, 0xbf60028b, v111
	v_cvt_pk_bf16_f32 v116, v112, v113
	v_cvt_pk_bf16_f32 v117, v114, v115
	v_exp_f32_e32 v108, v108
	v_exp_f32_e32 v109, v109
	v_exp_f32_e32 v110, v110
	v_exp_f32_e32 v111, v111
	v_cvt_pk_bf16_f32 v118, v104, v105
	v_cvt_pk_bf16_f32 v119, v106, v107
	global_store_dwordx2 v136, v[116:117], s[44:45]
	global_store_dwordx2 v136, v[118:119], s[46:47]
	global_store_dwordx4 v135, v[108:111], s[54:55]
	v_add_u32_e32 v136, 32, v136
	v_add_u32_e32 v135, 64, v135
	s_movk_i32 s2, 6
; __device__ __forceinline__ unsigned pk2(float lo, float hi) { f32x2 v = {lo, hi}; bf16x2_t b = __builtin_convertvector(v, bf16x2_t); return __builtin_bit_cast(unsigned, b); }
; __device__ __forceinline__ float sigmoidf_(float x) { return frcp(1.f + fexp2(-1.4426950408889634f * x)); }
; __device__ __forceinline__ void phase_lora(const Ctx& p, LAS unsigned char* lds) {
;     ...
;         auto tile = [&](const WF& f, int nt) {
;             f32x4 aw = (f32x4){0.f, 0.f, 0.f, 0.f}, aa = aw, ag = aw;
; #pragma unroll
;             for (int ks = 0; ks < 2; ++ks) { aw = __builtin_amdgcn_mfma_f32_16x16x32_bf16(f.w[ks], bx[ks], aw, 0, 0, 0); aa = __builtin_amdgcn_mfma_f32_16x16x32_bf16(f.a[ks], bx[2 + ks], aa, 0, 0, 0); }
; #pragma unroll
;             for (int ks = 0; ks < 4; ++ks) ag = __builtin_amdgcn_mfma_f32_16x16x32_bf16(f.gq[ks], bx[4 + ks], ag, 0, 0, 0);
;             const int c = nt * 16 + 4 * g;
;             f32x4 dec; float av[4];
; #pragma unroll
;             for (int e = 0; e < 4; ++e) {
;                 const float x = f.w0[e] + aw[e];
;                 const float sp = fmaxf(-x, 0.f) + log1pf(expf(-fabsf(x)));
;                 dec[e] = expf(-expf(-sp - 0.5f));
;                 av[e] = sigmoidf_(f.a0[e] + aa[e]);
;             }
;             *(f32x4*)(DEC + (size_t)row * 512 + c) = dec;
;             *(u32x2*)(AB + (size_t)row * 512 + c) = (u32x2){pk2(av[0], av[1]), pk2(av[2], av[3])};
;             *(u32x2*)(GG + (size_t)row * 512 + c) = (u32x2){pk2(ag[0], ag[1]), pk2(ag[2], ag[3])};
;         };
;         WF fa, fb;
;         ldw(fa, 0);
; #pragma unroll 1
;         for (int nt = 0; nt < 32; nt += 2) {
;             ldw(fb, nt + 1);
;             tile(fa, nt);
;             ldw(fa, (nt + 2) & 31);
;             tile(fb, nt + 1);
;         }
.Llora_nt:
	global_load_dwordx4 v[56:59], v132, s[24:25]
	global_load_dwordx4 v[60:63], v132, s[24:25] offset:64
	global_load_dwordx4 v[64:67], v132, s[40:41]
	global_load_dwordx4 v[68:71], v132, s[40:41] offset:64
	global_load_dwordx4 v[72:75], v133, s[42:43]
	global_load_dwordx4 v[76:79], v133, s[42:43] offset:64
	global_load_dwordx4 v[80:83], v133, s[42:43] offset:128
	global_load_dwordx4 v[84:87], v133, s[42:43] offset:192
	global_load_dwordx4 v[88:91], v134, s[20:21]
	global_load_dwordx4 v[92:95], v134, s[22:23]
	s_waitcnt vmcnt(13)
	v_mfma_f32_16x16x32_bf16 v[96:99], v[16:19], v[184:187], 0
	v_mfma_f32_16x16x32_bf16 v[100:103], v[24:27], v[192:195], 0
	v_mfma_f32_16x16x32_bf16 v[104:107], v[32:35], v[200:203], 0
	v_mfma_f32_16x16x32_bf16 v[96:99], v[20:23], v[188:191], v[96:99]
	v_mfma_f32_16x16x32_bf16 v[100:103], v[28:31], v[196:199], v[100:103]
	v_mfma_f32_16x16x32_bf16 v[104:107], v[36:39], v[204:207], v[104:107]
	v_mfma_f32_16x16x32_bf16 v[104:107], v[40:43], v[208:211], v[104:107]
	v_mfma_f32_16x16x32_bf16 v[104:107], v[44:47], v[212:215], v[104:107]
	v_add_u32_e32 v132, 0x800, v132
	v_add_u32_e32 v133, 0x1000, v133
	v_add_u32_e32 v134, 64, v134
	s_nop 4
	v_add_f32_e32 v108, v48, v96
	v_add_f32_e32 v109, v49, v97
	v_add_f32_e32 v110, v50, v98
	v_add_f32_e32 v111, v51, v99
	v_add_f32_e32 v112, v52, v100
	v_add_f32_e32 v113, v53, v101
	v_add_f32_e32 v114, v54, v102
	v_add_f32_e32 v115, v55, v103
	v_mul_f32_e32 v108, 0xbfb8aa3b, v108
	v_mul_f32_e32 v109, 0xbfb8aa3b, v109
	v_mul_f32_e32 v110, 0xbfb8aa3b, v110
	v_mul_f32_e32 v111, 0xbfb8aa3b, v111
	v_mul_f32_e32 v112, 0xbfb8aa3b, v112
	v_mul_f32_e32 v113, 0xbfb8aa3b, v113
	v_mul_f32_e32 v114, 0xbfb8aa3b, v114
	v_mul_f32_e32 v115, 0xbfb8aa3b, v115
	v_exp_f32_e32 v108, v108
	v_exp_f32_e32 v109, v109
	v_exp_f32_e32 v110, v110
	v_exp_f32_e32 v111, v111
	v_exp_f32_e32 v112, v112
	v_exp_f32_e32 v113, v113
	v_exp_f32_e32 v114, v114
	v_exp_f32_e32 v115, v115
	v_add_f32_e32 v108, 1.0, v108
	v_add_f32_e32 v109, 1.0, v109
	v_add_f32_e32 v110, 1.0, v110
	v_add_f32_e32 v111, 1.0, v111
	v_add_f32_e32 v112, 1.0, v112
	v_add_f32_e32 v113, 1.0, v113
	v_add_f32_e32 v114, 1.0, v114
	v_add_f32_e32 v115, 1.0, v115
	v_rcp_f32_e32 v108, v108
	v_rcp_f32_e32 v109, v109
	v_rcp_f32_e32 v110, v110
	v_rcp_f32_e32 v111, v111
	v_rcp_f32_e32 v112, v112
	v_rcp_f32_e32 v113, v113
	v_rcp_f32_e32 v114, v114
	v_rcp_f32_e32 v115, v115
	v_mul_f32_e32 v108, 0xbf60028b, v108
	v_mul_f32_e32 v109, 0xbf60028b, v109
	v_mul_f32_e32 v110, 0xbf60028b, v110
	v_mul_f32_e32 v111, 0xbf60028b, v111
	v_cvt_pk_bf16_f32 v116, v112, v113
	v_cvt_pk_bf16_f32 v117, v114, v115
	v_exp_f32_e32 v108, v108
	v_exp_f32_e32 v109, v109
	v_exp_f32_e32 v110, v110
	v_exp_f32_e32 v111, v111
	v_cvt_pk_bf16_f32 v118, v104, v105
	v_cvt_pk_bf16_f32 v119, v106, v107
	global_store_dwordx2 v136, v[116:117], s[44:45]
	global_store_dwordx2 v136, v[118:119], s[46:47]
	global_store_dwordx4 v135, v[108:111], s[54:55]
	v_add_u32_e32 v136, 32, v136
	v_add_u32_e32 v135, 64, v135
	global_load_dwordx4 v[16:19], v132, s[24:25]
	global_load_dwordx4 v[20:23], v132, s[24:25] offset:64
	global_load_dwordx4 v[24:27], v132, s[40:41]
	global_load_dwordx4 v[28:31], v132, s[40:41] offset:64
	global_load_dwordx4 v[32:35], v133, s[42:43]
	global_load_dwordx4 v[36:39], v133, s[42:43] offset:64
	global_load_dwordx4 v[40:43], v133, s[42:43] offset:128
	global_load_dwordx4 v[44:47], v133, s[42:43] offset:192
	global_load_dwordx4 v[48:51], v134, s[20:21]
	global_load_dwordx4 v[52:55], v134, s[22:23]
	s_waitcnt vmcnt(13)
	v_mfma_f32_16x16x32_bf16 v[96:99], v[56:59], v[184:187], 0
	v_mfma_f32_16x16x32_bf16 v[100:103], v[64:67], v[192:195], 0
	v_mfma_f32_16x16x32_bf16 v[104:107], v[72:75], v[200:203], 0
	v_mfma_f32_16x16x32_bf16 v[96:99], v[60:63], v[188:191], v[96:99]
	v_mfma_f32_16x16x32_bf16 v[100:103], v[68:71], v[196:199], v[100:103]
	v_mfma_f32_16x16x32_bf16 v[104:107], v[76:79], v[204:207], v[104:107]
	v_mfma_f32_16x16x32_bf16 v[104:107], v[80:83], v[208:211], v[104:107]
	v_mfma_f32_16x16x32_bf16 v[104:107], v[84:87], v[212:215], v[104:107]
	v_add_u32_e32 v132, 0x800, v132
	v_add_u32_e32 v133, 0x1000, v133
	v_add_u32_e32 v134, 64, v134
	s_nop 4
	v_add_f32_e32 v108, v88, v96
	v_add_f32_e32 v109, v89, v97
	v_add_f32_e32 v110, v90, v98
	v_add_f32_e32 v111, v91, v99
	v_add_f32_e32 v112, v92, v100
	v_add_f32_e32 v113, v93, v101
	v_add_f32_e32 v114, v94, v102
	v_add_f32_e32 v115, v95, v103
	v_mul_f32_e32 v108, 0xbfb8aa3b, v108
	v_mul_f32_e32 v109, 0xbfb8aa3b, v109
	v_mul_f32_e32 v110, 0xbfb8aa3b, v110
	v_mul_f32_e32 v111, 0xbfb8aa3b, v111
	v_mul_f32_e32 v112, 0xbfb8aa3b, v112
	v_mul_f32_e32 v113, 0xbfb8aa3b, v113
	v_mul_f32_e32 v114, 0xbfb8aa3b, v114
	v_mul_f32_e32 v115, 0xbfb8aa3b, v115
	v_exp_f32_e32 v108, v108
	v_exp_f32_e32 v109, v109
	v_exp_f32_e32 v110, v110
	v_exp_f32_e32 v111, v111
	v_exp_f32_e32 v112, v112
	v_exp_f32_e32 v113, v113
	v_exp_f32_e32 v114, v114
	v_exp_f32_e32 v115, v115
	v_add_f32_e32 v108, 1.0, v108
	v_add_f32_e32 v109, 1.0, v109
	v_add_f32_e32 v110, 1.0, v110
	v_add_f32_e32 v111, 1.0, v111
	v_add_f32_e32 v112, 1.0, v112
	v_add_f32_e32 v113, 1.0, v113
	v_add_f32_e32 v114, 1.0, v114
	v_add_f32_e32 v115, 1.0, v115
	v_rcp_f32_e32 v108, v108
	v_rcp_f32_e32 v109, v109
	v_rcp_f32_e32 v110, v110
	v_rcp_f32_e32 v111, v111
	v_rcp_f32_e32 v112, v112
	v_rcp_f32_e32 v113, v113
	v_rcp_f32_e32 v114, v114
	v_rcp_f32_e32 v115, v115
	v_mul_f32_e32 v108, 0xbf60028b, v108
	v_mul_f32_e32 v109, 0xbf60028b, v109
	v_mul_f32_e32 v110, 0xbf60028b, v110
	v_mul_f32_e32 v111, 0xbf60028b, v111
	v_cvt_pk_bf16_f32 v116, v112, v113
	v_cvt_pk_bf16_f32 v117, v114, v115
	v_exp_f32_e32 v108, v108
	v_exp_f32_e32 v109, v109
	v_exp_f32_e32 v110, v110
	v_exp_f32_e32 v111, v111
	v_cvt_pk_bf16_f32 v118, v104, v105
	v_cvt_pk_bf16_f32 v119, v106, v107
	global_store_dwordx2 v136, v[116:117], s[44:45]
	global_store_dwordx2 v136, v[118:119], s[46:47]
	global_store_dwordx4 v135, v[108:111], s[54:55]
	v_add_u32_e32 v136, 32, v136
	v_add_u32_e32 v135, 64, v135
	s_sub_u32 s2, s2, 1
	s_cmp_lg_u32 s2, 0
	s_cbranch_scc1 .Llora_nt
; __device__ __forceinline__ unsigned pk2(float lo, float hi) { f32x2 v = {lo, hi}; bf16x2_t b = __builtin_convertvector(v, bf16x2_t); return __builtin_bit_cast(unsigned, b); }
; __device__ __forceinline__ float sigmoidf_(float x) { return frcp(1.f + fexp2(-1.4426950408889634f * x)); }
; __device__ __forceinline__ void phase_lora(const Ctx& p, LAS unsigned char* lds) {
;     ...
;     for (int it = blockIdx.x + gridDim.x * wave; it < MR / 16; it += gridDim.x * 8) {
;         const int r0 = it * 16;
;     ...
;         auto tile = [&](const WF& f, int nt) {
;             f32x4 aw = (f32x4){0.f, 0.f, 0.f, 0.f}, aa = aw, ag = aw;
; #pragma unroll
;             for (int ks = 0; ks < 2; ++ks) { aw = __builtin_amdgcn_mfma_f32_16x16x32_bf16(f.w[ks], bx[ks], aw, 0, 0, 0); aa = __builtin_amdgcn_mfma_f32_16x16x32_bf16(f.a[ks], bx[2 + ks], aa, 0, 0, 0); }
; #pragma unroll
;             for (int ks = 0; ks < 4; ++ks) ag = __builtin_amdgcn_mfma_f32_16x16x32_bf16(f.gq[ks], bx[4 + ks], ag, 0, 0, 0);
;             const int c = nt * 16 + 4 * g;
;             f32x4 dec; float av[4];
; #pragma unroll
;             for (int e = 0; e < 4; ++e) {
;                 const float x = f.w0[e] + aw[e];
;                 const float sp = fmaxf(-x, 0.f) + log1pf(expf(-fabsf(x)));
;                 dec[e] = expf(-expf(-sp - 0.5f));
;                 av[e] = sigmoidf_(f.a0[e] + aa[e]);
;             }
;             *(f32x4*)(DEC + (size_t)row * 512 + c) = dec;
;             *(u32x2*)(AB + (size_t)row * 512 + c) = (u32x2){pk2(av[0], av[1]), pk2(av[2], av[3])};
;             *(u32x2*)(GG + (size_t)row * 512 + c) = (u32x2){pk2(ag[0], ag[1]), pk2(ag[2], ag[3])};
;         };
;         WF fa, fb;
;         ldw(fa, 0);
; #pragma unroll 1
;         for (int nt = 0; nt < 32; nt += 2) {
;             ldw(fb, nt + 1);
;             tile(fa, nt);
;             ldw(fa, (nt + 2) & 31);
;             tile(fb, nt + 1);
	global_load_dwordx4 v[56:59], v132, s[24:25]
	global_load_dwordx4 v[60:63], v132, s[24:25] offset:64
	global_load_dwordx4 v[64:67], v132, s[40:41]
	global_load_dwordx4 v[68:71], v132, s[40:41] offset:64
	global_load_dwordx4 v[72:75], v133, s[42:43]
	global_load_dwordx4 v[76:79], v133, s[42:43] offset:64
	global_load_dwordx4 v[80:83], v133, s[42:43] offset:128
	global_load_dwordx4 v[84:87], v133, s[42:43] offset:192
	global_load_dwordx4 v[88:91], v134, s[20:21]
	global_load_dwordx4 v[92:95], v134, s[22:23]
	s_waitcnt vmcnt(13)
	v_mfma_f32_16x16x32_bf16 v[96:99], v[16:19], v[184:187], 0
	v_mfma_f32_16x16x32_bf16 v[100:103], v[24:27], v[192:195], 0
	v_mfma_f32_16x16x32_bf16 v[104:107], v[32:35], v[200:203], 0
	v_mfma_f32_16x16x32_bf16 v[96:99], v[20:23], v[188:191], v[96:99]
	v_mfma_f32_16x16x32_bf16 v[100:103], v[28:31], v[196:199], v[100:103]
	v_mfma_f32_16x16x32_bf16 v[104:107], v[36:39], v[204:207], v[104:107]
	v_mfma_f32_16x16x32_bf16 v[104:107], v[40:43], v[208:211], v[104:107]
	v_mfma_f32_16x16x32_bf16 v[104:107], v[44:47], v[212:215], v[104:107]
	v_add_u32_e32 v132, 0x800, v132
	v_add_u32_e32 v133, 0x1000, v133
	v_add_u32_e32 v134, 64, v134
	s_nop 4
	v_add_f32_e32 v108, v48, v96
	v_add_f32_e32 v109, v49, v97
	v_add_f32_e32 v110, v50, v98
	v_add_f32_e32 v111, v51, v99
	v_add_f32_e32 v112, v52, v100
	v_add_f32_e32 v113, v53, v101
	v_add_f32_e32 v114, v54, v102
	v_add_f32_e32 v115, v55, v103
	v_mul_f32_e32 v108, 0xbfb8aa3b, v108
	v_mul_f32_e32 v109, 0xbfb8aa3b, v109
	v_mul_f32_e32 v110, 0xbfb8aa3b, v110
	v_mul_f32_e32 v111, 0xbfb8aa3b, v111
	v_mul_f32_e32 v112, 0xbfb8aa3b, v112
	v_mul_f32_e32 v113, 0xbfb8aa3b, v113
	v_mul_f32_e32 v114, 0xbfb8aa3b, v114
	v_mul_f32_e32 v115, 0xbfb8aa3b, v115
	v_exp_f32_e32 v108, v108
	v_exp_f32_e32 v109, v109
	v_exp_f32_e32 v110, v110
	v_exp_f32_e32 v111, v111
	v_exp_f32_e32 v112, v112
	v_exp_f32_e32 v113, v113
	v_exp_f32_e32 v114, v114
	v_exp_f32_e32 v115, v115
	v_add_f32_e32 v108, 1.0, v108
	v_add_f32_e32 v109, 1.0, v109
	v_add_f32_e32 v110, 1.0, v110
	v_add_f32_e32 v111, 1.0, v111
	v_add_f32_e32 v112, 1.0, v112
	v_add_f32_e32 v113, 1.0, v113
	v_add_f32_e32 v114, 1.0, v114
	v_add_f32_e32 v115, 1.0, v115
	v_rcp_f32_e32 v108, v108
	v_rcp_f32_e32 v109, v109
	v_rcp_f32_e32 v110, v110
	v_rcp_f32_e32 v111, v111
	v_rcp_f32_e32 v112, v112
	v_rcp_f32_e32 v113, v113
	v_rcp_f32_e32 v114, v114
	v_rcp_f32_e32 v115, v115
	v_mul_f32_e32 v108, 0xbf60028b, v108
	v_mul_f32_e32 v109, 0xbf60028b, v109
	v_mul_f32_e32 v110, 0xbf60028b, v110
	v_mul_f32_e32 v111, 0xbf60028b, v111
	v_cvt_pk_bf16_f32 v116, v112, v113
	v_cvt_pk_bf16_f32 v117, v114, v115
	v_exp_f32_e32 v108, v108
	v_exp_f32_e32 v109, v109
	v_exp_f32_e32 v110, v110
	v_exp_f32_e32 v111, v111
	v_cvt_pk_bf16_f32 v118, v104, v105
	v_cvt_pk_bf16_f32 v119, v106, v107
	global_store_dwordx2 v136, v[116:117], s[44:45]
	global_store_dwordx2 v136, v[118:119], s[46:47]
	global_store_dwordx4 v135, v[108:111], s[54:55]
	v_add_u32_e32 v136, 32, v136
	v_add_u32_e32 v135, 64, v135
	s_waitcnt vmcnt(3)
	v_mfma_f32_16x16x32_bf16 v[96:99], v[56:59], v[184:187], 0
	v_mfma_f32_16x16x32_bf16 v[100:103], v[64:67], v[192:195], 0
	v_mfma_f32_16x16x32_bf16 v[104:107], v[72:75], v[200:203], 0
	v_mfma_f32_16x16x32_bf16 v[96:99], v[60:63], v[188:191], v[96:99]
	v_mfma_f32_16x16x32_bf16 v[100:103], v[68:71], v[196:199], v[100:103]
	v_mfma_f32_16x16x32_bf16 v[104:107], v[76:79], v[204:207], v[104:107]
	v_mfma_f32_16x16x32_bf16 v[104:107], v[80:83], v[208:211], v[104:107]
	v_mfma_f32_16x16x32_bf16 v[104:107], v[84:87], v[212:215], v[104:107]
	v_add_u32_e32 v132, 0x800, v132
	v_add_u32_e32 v133, 0x1000, v133
	v_add_u32_e32 v134, 64, v134
	s_nop 4
	v_add_f32_e32 v108, v88, v96
	v_add_f32_e32 v109, v89, v97
	v_add_f32_e32 v110, v90, v98
	v_add_f32_e32 v111, v91, v99
	v_add_f32_e32 v112, v92, v100
	v_add_f32_e32 v113, v93, v101
	v_add_f32_e32 v114, v94, v102
	v_add_f32_e32 v115, v95, v103
	v_mul_f32_e32 v108, 0xbfb8aa3b, v108
	v_mul_f32_e32 v109, 0xbfb8aa3b, v109
	v_mul_f32_e32 v110, 0xbfb8aa3b, v110
	v_mul_f32_e32 v111, 0xbfb8aa3b, v111
	v_mul_f32_e32 v112, 0xbfb8aa3b, v112
	v_mul_f32_e32 v113, 0xbfb8aa3b, v113
	v_mul_f32_e32 v114, 0xbfb8aa3b, v114
	v_mul_f32_e32 v115, 0xbfb8aa3b, v115
	v_exp_f32_e32 v108, v108
	v_exp_f32_e32 v109, v109
	v_exp_f32_e32 v110, v110
	v_exp_f32_e32 v111, v111
	v_exp_f32_e32 v112, v112
	v_exp_f32_e32 v113, v113
	v_exp_f32_e32 v114, v114
	v_exp_f32_e32 v115, v115
	v_add_f32_e32 v108, 1.0, v108
	v_add_f32_e32 v109, 1.0, v109
	v_add_f32_e32 v110, 1.0, v110
	v_add_f32_e32 v111, 1.0, v111
	v_add_f32_e32 v112, 1.0, v112
	v_add_f32_e32 v113, 1.0, v113
	v_add_f32_e32 v114, 1.0, v114
	v_add_f32_e32 v115, 1.0, v115
	v_rcp_f32_e32 v108, v108
	v_rcp_f32_e32 v109, v109
	v_rcp_f32_e32 v110, v110
	v_rcp_f32_e32 v111, v111
	v_rcp_f32_e32 v112, v112
	v_rcp_f32_e32 v113, v113
	v_rcp_f32_e32 v114, v114
	v_rcp_f32_e32 v115, v115
	v_mul_f32_e32 v108, 0xbf60028b, v108
	v_mul_f32_e32 v109, 0xbf60028b, v109
	v_mul_f32_e32 v110, 0xbf60028b, v110
	v_mul_f32_e32 v111, 0xbf60028b, v111
	v_cvt_pk_bf16_f32 v116, v112, v113
	v_cvt_pk_bf16_f32 v117, v114, v115
	v_exp_f32_e32 v108, v108
	v_exp_f32_e32 v109, v109
	v_exp_f32_e32 v110, v110
	v_exp_f32_e32 v111, v111
	v_cvt_pk_bf16_f32 v118, v104, v105
	v_cvt_pk_bf16_f32 v119, v106, v107
	global_store_dwordx2 v136, v[116:117], s[44:45]
	global_store_dwordx2 v136, v[118:119], s[46:47]
	global_store_dwordx4 v135, v[108:111], s[54:55]
	v_add_u32_e32 v136, 32, v136
	v_add_u32_e32 v135, 64, v135
	s_cmp_lt_u32 s28, 32
	s_cbranch_scc0 .Llora_done
	s_mov_b32 s57, 1
	s_lshr_b32 s2, s28, 2
	s_add_i32 s26, s2, 0x400
	s_branch .Llora_item
; __device__ __forceinline__ unsigned pk2(float lo, float hi) { f32x2 v = {lo, hi}; bf16x2_t b = __builtin_convertvector(v, bf16x2_t); return __builtin_bit_cast(unsigned, b); }
; __device__ __forceinline__ float sigmoidf_(float x) { return frcp(1.f + fexp2(-1.4426950408889634f * x)); }
;     __device__ __forceinline__ const float* in(int i) const { return (const float*)ptr(i); }
; __device__ __forceinline__ void phase_lora(const Ctx& p, LAS unsigned char* lds) {
;     ...
;         auto ldw = [&](WF& f, int nt) {
;             const int n = nt * 16 + q, c = nt * 16 + 4 * g;
; #pragma unroll
;             for (int ks = 0; ks < 2; ++ks) { f.w[ks] = *(const bf16x8*)(w2T + n * 64 + ks * 32 + 8 * g); f.a[ks] = *(const bf16x8*)(a2T + n * 64 + ks * 32 + 8 * g); }
; #pragma unroll
;             for (int ks = 0; ks < 4; ++ks) f.gq[ks] = *(const bf16x8*)(g2T + n * 128 + ks * 32 + 8 * g);
;             f.w0 = *(const f32x4*)(p.in(18) + c); f.a0 = *(const f32x4*)(p.in(20) + c);
;         };
;         auto tile = [&](const WF& f, int nt) {
;             f32x4 aw = (f32x4){0.f, 0.f, 0.f, 0.f}, aa = aw, ag = aw;
; #pragma unroll
;             for (int ks = 0; ks < 2; ++ks) { aw = __builtin_amdgcn_mfma_f32_16x16x32_bf16(f.w[ks], bx[ks], aw, 0, 0, 0); aa = __builtin_amdgcn_mfma_f32_16x16x32_bf16(f.a[ks], bx[2 + ks], aa, 0, 0, 0); }
; #pragma unroll
;             for (int ks = 0; ks < 4; ++ks) ag = __builtin_amdgcn_mfma_f32_16x16x32_bf16(f.gq[ks], bx[4 + ks], ag, 0, 0, 0);
;             const int c = nt * 16 + 4 * g;
;             f32x4 dec; float av[4];
; #pragma unroll
;             for (int e = 0; e < 4; ++e) {
;                 const float x = f.w0[e] + aw[e];
;                 const float sp = fmaxf(-x, 0.f) + log1pf(expf(-fabsf(x)));
;                 dec[e] = expf(-expf(-sp - 0.5f));
;                 av[e] = sigmoidf_(f.a0[e] + aa[e]);
;             }
;             *(f32x4*)(DEC + (size_t)row * 512 + c) = dec;
;             *(u32x2*)(AB + (size_t)row * 512 + c) = (u32x2){pk2(av[0], av[1]), pk2(av[2], av[3])};
;             *(u32x2*)(GG + (size_t)row * 512 + c) = (u32x2){pk2(ag[0], ag[1]), pk2(ag[2], ag[3])};
;         };
.Llora_single:
	s_and_b32 s2, s28, 3
	s_lshl_b32 s2, s2, 3
	s_add_i32 s2, s2, s27
	s_lshl_b32 s3, s2, 11
	v_add_u32_e32 v132, s3, v132
	s_lshl_b32 s3, s2, 12
	v_add_u32_e32 v133, s3, v133
	s_lshl_b32 s3, s2, 6
	v_add_u32_e32 v134, s3, v134
	v_add_u32_e32 v135, s3, v135
	s_lshl_b32 s3, s2, 5
	v_add_u32_e32 v136, s3, v136
	global_load_dwordx4 v[16:19], v132, s[24:25]
	global_load_dwordx4 v[20:23], v132, s[24:25] offset:64
	global_load_dwordx4 v[24:27], v132, s[40:41]
	global_load_dwordx4 v[28:31], v132, s[40:41] offset:64
	global_load_dwordx4 v[32:35], v133, s[42:43]
	global_load_dwordx4 v[36:39], v133, s[42:43] offset:64
	global_load_dwordx4 v[40:43], v133, s[42:43] offset:128
	global_load_dwordx4 v[44:47], v133, s[42:43] offset:192
	global_load_dwordx4 v[48:51], v134, s[20:21]
	global_load_dwordx4 v[52:55], v134, s[22:23]
	s_waitcnt lgkmcnt(0)
	s_waitcnt vmcnt(0)
	v_mfma_f32_16x16x32_bf16 v[96:99], v[16:19], v[184:187], 0
	v_mfma_f32_16x16x32_bf16 v[100:103], v[24:27], v[192:195], 0
	v_mfma_f32_16x16x32_bf16 v[104:107], v[32:35], v[200:203], 0
	v_mfma_f32_16x16x32_bf16 v[96:99], v[20:23], v[188:191], v[96:99]
	v_mfma_f32_16x16x32_bf16 v[100:103], v[28:31], v[196:199], v[100:103]
	v_mfma_f32_16x16x32_bf16 v[104:107], v[36:39], v[204:207], v[104:107]
	v_mfma_f32_16x16x32_bf16 v[104:107], v[40:43], v[208:211], v[104:107]
	v_mfma_f32_16x16x32_bf16 v[104:107], v[44:47], v[212:215], v[104:107]
	v_add_u32_e32 v132, 0x800, v132
	v_add_u32_e32 v133, 0x1000, v133
	v_add_u32_e32 v134, 64, v134
	s_nop 4
	v_add_f32_e32 v108, v48, v96
	v_add_f32_e32 v109, v49, v97
	v_add_f32_e32 v110, v50, v98
	v_add_f32_e32 v111, v51, v99
	v_add_f32_e32 v112, v52, v100
	v_add_f32_e32 v113, v53, v101
	v_add_f32_e32 v114, v54, v102
	v_add_f32_e32 v115, v55, v103
	v_mul_f32_e32 v108, 0xbfb8aa3b, v108
	v_mul_f32_e32 v109, 0xbfb8aa3b, v109
	v_mul_f32_e32 v110, 0xbfb8aa3b, v110
	v_mul_f32_e32 v111, 0xbfb8aa3b, v111
	v_mul_f32_e32 v112, 0xbfb8aa3b, v112
	v_mul_f32_e32 v113, 0xbfb8aa3b, v113
	v_mul_f32_e32 v114, 0xbfb8aa3b, v114
	v_mul_f32_e32 v115, 0xbfb8aa3b, v115
	v_exp_f32_e32 v108, v108
	v_exp_f32_e32 v109, v109
	v_exp_f32_e32 v110, v110
	v_exp_f32_e32 v111, v111
	v_exp_f32_e32 v112, v112
	v_exp_f32_e32 v113, v113
	v_exp_f32_e32 v114, v114
	v_exp_f32_e32 v115, v115
	v_add_f32_e32 v108, 1.0, v108
	v_add_f32_e32 v109, 1.0, v109
	v_add_f32_e32 v110, 1.0, v110
	v_add_f32_e32 v111, 1.0, v111
	v_add_f32_e32 v112, 1.0, v112
	v_add_f32_e32 v113, 1.0, v113
	v_add_f32_e32 v114, 1.0, v114
	v_add_f32_e32 v115, 1.0, v115
	v_rcp_f32_e32 v108, v108
	v_rcp_f32_e32 v109, v109
	v_rcp_f32_e32 v110, v110
	v_rcp_f32_e32 v111, v111
	v_rcp_f32_e32 v112, v112
	v_rcp_f32_e32 v113, v113
	v_rcp_f32_e32 v114, v114
	v_rcp_f32_e32 v115, v115
	v_mul_f32_e32 v108, 0xbf60028b, v108
	v_mul_f32_e32 v109, 0xbf60028b, v109
	v_mul_f32_e32 v110, 0xbf60028b, v110
	v_mul_f32_e32 v111, 0xbf60028b, v111
	v_cvt_pk_bf16_f32 v116, v112, v113
	v_cvt_pk_bf16_f32 v117, v114, v115
	v_exp_f32_e32 v108, v108
	v_exp_f32_e32 v109, v109
	v_exp_f32_e32 v110, v110
	v_exp_f32_e32 v111, v111
	v_cvt_pk_bf16_f32 v118, v104, v105
	v_cvt_pk_bf16_f32 v119, v106, v107
	global_store_dwordx2 v136, v[116:117], s[44:45]
	global_store_dwordx2 v136, v[118:119], s[46:47]
	global_store_dwordx4 v135, v[108:111], s[54:55]
	v_add_u32_e32 v136, 32, v136
	v_add_u32_e32 v135, 64, v135
	s_branch .Llora_done
